# tail-prefetch elision: skip the next-tile DMA prefetch on the last K-tile of each block's last GEMM tile
# baseline (speedup 1.0000x reference)
.Lggu0_wd:
	s_barrier
	ds_read_b128 v[184:187], v116 offset:0
	ds_read_b128 v[204:207], v119 offset:20480
	ds_read_b128 v[208:211], v119 offset:22528
	ds_read_b128 v[212:215], v119 offset:24576
	ds_read_b128 v[216:219], v119 offset:26624
	ds_read_b128 v[188:191], v116 offset:2048
	ds_read_b128 v[192:195], v116 offset:4096
	ds_read_b128 v[196:199], v116 offset:6144
	ds_read_b128 v[200:203], v116 offset:8192
	s_waitcnt lgkmcnt(7)
	v_mfma_f32_16x16x32_bf16 v[0:3], v[204:207], v[184:187], v[0:3]
	s_add_u32 m0, s13, 0x9000
	s_nop 0
	global_load_lds_dwordx4 v165, s[24:25]
	s_waitcnt lgkmcnt(6)
	v_mfma_f32_16x16x32_bf16 v[4:7], v[208:211], v[184:187], v[4:7]
	s_add_u32 m0, s13, 0xa000
	v_add_u32_e32 v166, 0x2000, v165
	global_load_lds_dwordx4 v166, s[24:25]
	s_waitcnt lgkmcnt(5)
	v_mfma_f32_16x16x32_bf16 v[8:11], v[212:215], v[184:187], v[8:11]
	s_add_u32 m0, s13, 0xb000
	v_add_u32_e32 v166, 0x10000, v165
	global_load_lds_dwordx4 v166, s[24:25]
	s_waitcnt lgkmcnt(4)
	v_mfma_f32_16x16x32_bf16 v[12:15], v[216:219], v[184:187], v[12:15]
	s_add_u32 m0, s13, 0xc000
	v_add_u32_e32 v166, 0x12000, v165
	global_load_lds_dwordx4 v166, s[24:25]
	ds_read_b128 v[220:223], v118 offset:0
	ds_read_b128 v[240:243], v160 offset:20480
	ds_read_b128 v[244:247], v160 offset:22528
	ds_read_b128 v[248:251], v160 offset:24576
	ds_read_b128 v[252:255], v160 offset:26624
	s_waitcnt lgkmcnt(8)
	v_mfma_f32_16x16x32_bf16 v[16:19], v[204:207], v[188:191], v[16:19]
	v_mfma_f32_16x16x32_bf16 v[20:23], v[208:211], v[188:191], v[20:23]
	v_mfma_f32_16x16x32_bf16 v[24:27], v[212:215], v[188:191], v[24:27]
	v_mfma_f32_16x16x32_bf16 v[28:31], v[216:219], v[188:191], v[28:31]
	ds_read_b128 v[224:227], v118 offset:2048
	ds_read_b128 v[228:231], v118 offset:4096
	ds_read_b128 v[232:235], v118 offset:6144
	ds_read_b128 v[236:239], v118 offset:8192
	s_waitcnt lgkmcnt(11)
	v_mfma_f32_16x16x32_bf16 v[32:35], v[204:207], v[192:195], v[32:35]
	v_mfma_f32_16x16x32_bf16 v[36:39], v[208:211], v[192:195], v[36:39]
	v_mfma_f32_16x16x32_bf16 v[40:43], v[212:215], v[192:195], v[40:43]
	v_mfma_f32_16x16x32_bf16 v[44:47], v[216:219], v[192:195], v[44:47]
	s_waitcnt lgkmcnt(10)
	v_mfma_f32_16x16x32_bf16 v[48:51], v[204:207], v[196:199], v[48:51]
	v_mfma_f32_16x16x32_bf16 v[52:55], v[208:211], v[196:199], v[52:55]
	v_mfma_f32_16x16x32_bf16 v[56:59], v[212:215], v[196:199], v[56:59]
	v_mfma_f32_16x16x32_bf16 v[60:63], v[216:219], v[196:199], v[60:63]
	s_waitcnt lgkmcnt(9)
	v_mfma_f32_16x16x32_bf16 v[64:67], v[204:207], v[200:203], v[64:67]
	v_mfma_f32_16x16x32_bf16 v[68:71], v[208:211], v[200:203], v[68:71]
	v_mfma_f32_16x16x32_bf16 v[72:75], v[212:215], v[200:203], v[72:75]
	v_mfma_f32_16x16x32_bf16 v[76:79], v[216:219], v[200:203], v[76:79]
	s_waitcnt lgkmcnt(7)
	v_mfma_f32_16x16x32_bf16 v[0:3], v[240:243], v[220:223], v[0:3]
	s_waitcnt lgkmcnt(6)
	v_mfma_f32_16x16x32_bf16 v[4:7], v[244:247], v[220:223], v[4:7]
	s_waitcnt lgkmcnt(5)
	v_mfma_f32_16x16x32_bf16 v[8:11], v[248:251], v[220:223], v[8:11]
	s_waitcnt lgkmcnt(4)
	v_mfma_f32_16x16x32_bf16 v[12:15], v[252:255], v[220:223], v[12:15]
	s_waitcnt lgkmcnt(3)
	v_mfma_f32_16x16x32_bf16 v[16:19], v[240:243], v[224:227], v[16:19]
	v_mfma_f32_16x16x32_bf16 v[20:23], v[244:247], v[224:227], v[20:23]
	v_mfma_f32_16x16x32_bf16 v[24:27], v[248:251], v[224:227], v[24:27]
	v_mfma_f32_16x16x32_bf16 v[28:31], v[252:255], v[224:227], v[28:31]
	s_waitcnt lgkmcnt(2)
	v_mfma_f32_16x16x32_bf16 v[32:35], v[240:243], v[228:231], v[32:35]
	v_mfma_f32_16x16x32_bf16 v[36:39], v[244:247], v[228:231], v[36:39]
	v_mfma_f32_16x16x32_bf16 v[40:43], v[248:251], v[228:231], v[40:43]
	v_mfma_f32_16x16x32_bf16 v[44:47], v[252:255], v[228:231], v[44:47]
	s_waitcnt lgkmcnt(1)
	v_mfma_f32_16x16x32_bf16 v[48:51], v[240:243], v[232:235], v[48:51]
	v_mfma_f32_16x16x32_bf16 v[52:55], v[244:247], v[232:235], v[52:55]
	v_mfma_f32_16x16x32_bf16 v[56:59], v[248:251], v[232:235], v[56:59]
	v_mfma_f32_16x16x32_bf16 v[60:63], v[252:255], v[232:235], v[60:63]
	s_add_u32 s24, s24, 0x80
	s_addc_u32 s25, s25, 0
	s_waitcnt lgkmcnt(0)
	v_mfma_f32_16x16x32_bf16 v[64:67], v[240:243], v[236:239], v[64:67]
	v_mfma_f32_16x16x32_bf16 v[68:71], v[244:247], v[236:239], v[68:71]
	v_mfma_f32_16x16x32_bf16 v[72:75], v[248:251], v[236:239], v[72:75]
	v_mfma_f32_16x16x32_bf16 v[76:79], v[252:255], v[236:239], v[76:79]
	s_waitcnt vmcnt(0)
	s_barrier
	ds_read_b128 v[184:187], v116 offset:0
	ds_read_b128 v[204:207], v119 offset:36864
	ds_read_b128 v[208:211], v119 offset:38912
	ds_read_b128 v[212:215], v119 offset:40960
	ds_read_b128 v[216:219], v119 offset:43008
	ds_read_b128 v[188:191], v116 offset:2048
	ds_read_b128 v[192:195], v116 offset:4096
	ds_read_b128 v[196:199], v116 offset:6144
	ds_read_b128 v[200:203], v116 offset:8192
	s_waitcnt lgkmcnt(7)
	v_mfma_f32_16x16x32_bf16 v[80:83], v[204:207], v[184:187], v[80:83]
	s_add_u32 m0, s13, 0xd100
	s_nop 0
	global_load_lds_dwordx4 v161, s[2:3] sc1
	s_waitcnt lgkmcnt(6)
	v_mfma_f32_16x16x32_bf16 v[84:87], v[208:211], v[184:187], v[84:87]
	s_add_u32 m0, s13, 0xe100
	v_add_u32_e32 v166, 0x10000, v161
	global_load_lds_dwordx4 v166, s[2:3] sc1
	s_waitcnt lgkmcnt(5)
	v_mfma_f32_16x16x32_bf16 v[88:91], v[212:215], v[184:187], v[88:91]
	s_add_u32 m0, s13, 0xf100
	v_add_u32_e32 v166, 0x20000, v161
	global_load_lds_dwordx4 v166, s[2:3] sc1
	s_waitcnt lgkmcnt(4)
	v_mfma_f32_16x16x32_bf16 v[92:95], v[216:219], v[184:187], v[92:95]
	s_add_u32 m0, s13, 0x10100
	v_add_u32_e32 v166, 0x30000, v161
	global_load_lds_dwordx4 v166, s[2:3] sc1
	ds_read_b128 v[220:223], v118 offset:0
	ds_read_b128 v[240:243], v160 offset:36864
	ds_read_b128 v[244:247], v160 offset:38912
	ds_read_b128 v[248:251], v160 offset:40960
	ds_read_b128 v[252:255], v160 offset:43008
	s_waitcnt lgkmcnt(8)
	v_mfma_f32_16x16x32_bf16 v[96:99], v[204:207], v[188:191], v[96:99]
	s_add_u32 m0, s13, 0x11100
	v_add_u32_e32 v166, 0x40000, v161
	global_load_lds_dwordx4 v166, s[2:3] sc1
	v_mfma_f32_16x16x32_bf16 v[100:103], v[208:211], v[188:191], v[100:103]
	s_add_u32 m0, s13, 0x5000
	s_nop 0
	global_load_lds_dwordx4 v165, s[6:7]
	v_mfma_f32_16x16x32_bf16 v[104:107], v[212:215], v[188:191], v[104:107]
	s_add_u32 m0, s13, 0x6000
	v_add_u32_e32 v166, 0x2000, v165
	global_load_lds_dwordx4 v166, s[6:7]
	v_mfma_f32_16x16x32_bf16 v[108:111], v[216:219], v[188:191], v[108:111]
	s_add_u32 m0, s13, 0x7000
	v_add_u32_e32 v166, 0x10000, v165
	global_load_lds_dwordx4 v166, s[6:7]
	ds_read_b128 v[224:227], v118 offset:2048
	ds_read_b128 v[228:231], v118 offset:4096
	ds_read_b128 v[232:235], v118 offset:6144
	ds_read_b128 v[236:239], v118 offset:8192
	s_waitcnt lgkmcnt(11)
	v_mfma_f32_16x16x32_bf16 v[112:115], v[204:207], v[192:195], v[112:115]
	s_add_u32 m0, s13, 0x8000
	v_add_u32_e32 v166, 0x12000, v165
	global_load_lds_dwordx4 v166, s[6:7]
	v_mfma_f32_16x16x32_bf16 v[120:123], v[208:211], v[192:195], v[120:123]
	v_mfma_f32_16x16x32_bf16 v[124:127], v[212:215], v[192:195], v[124:127]
	v_mfma_f32_16x16x32_bf16 v[140:143], v[216:219], v[192:195], v[140:143]
	s_waitcnt lgkmcnt(10)
	v_mfma_f32_16x16x32_bf16 v[144:147], v[204:207], v[196:199], v[144:147]
	v_mfma_f32_16x16x32_bf16 v[148:151], v[208:211], v[196:199], v[148:151]
	v_mfma_f32_16x16x32_bf16 v[152:155], v[212:215], v[196:199], v[152:155]
	v_mfma_f32_16x16x32_bf16 v[156:159], v[216:219], v[196:199], v[156:159]
	s_waitcnt lgkmcnt(9)
	v_mfma_f32_16x16x32_bf16 v[168:171], v[204:207], v[200:203], v[168:171]
	v_mfma_f32_16x16x32_bf16 v[172:175], v[208:211], v[200:203], v[172:175]
	v_mfma_f32_16x16x32_bf16 v[176:179], v[212:215], v[200:203], v[176:179]
	v_mfma_f32_16x16x32_bf16 v[180:183], v[216:219], v[200:203], v[180:183]
	s_waitcnt lgkmcnt(7)
	v_mfma_f32_16x16x32_bf16 v[80:83], v[240:243], v[220:223], v[80:83]
	s_waitcnt lgkmcnt(6)
	v_mfma_f32_16x16x32_bf16 v[84:87], v[244:247], v[220:223], v[84:87]
	s_waitcnt lgkmcnt(5)
	v_mfma_f32_16x16x32_bf16 v[88:91], v[248:251], v[220:223], v[88:91]
	s_waitcnt lgkmcnt(4)
	v_mfma_f32_16x16x32_bf16 v[92:95], v[252:255], v[220:223], v[92:95]
	s_waitcnt lgkmcnt(3)
	v_mfma_f32_16x16x32_bf16 v[96:99], v[240:243], v[224:227], v[96:99]
	v_mfma_f32_16x16x32_bf16 v[100:103], v[244:247], v[224:227], v[100:103]
	v_mfma_f32_16x16x32_bf16 v[104:107], v[248:251], v[224:227], v[104:107]
	v_mfma_f32_16x16x32_bf16 v[108:111], v[252:255], v[224:227], v[108:111]
	s_waitcnt lgkmcnt(2)
	v_mfma_f32_16x16x32_bf16 v[112:115], v[240:243], v[228:231], v[112:115]
	v_mfma_f32_16x16x32_bf16 v[120:123], v[244:247], v[228:231], v[120:123]
	v_mfma_f32_16x16x32_bf16 v[124:127], v[248:251], v[228:231], v[124:127]
	v_mfma_f32_16x16x32_bf16 v[140:143], v[252:255], v[228:231], v[140:143]
	s_waitcnt lgkmcnt(1)
	v_mfma_f32_16x16x32_bf16 v[144:147], v[240:243], v[232:235], v[144:147]
	v_mfma_f32_16x16x32_bf16 v[148:151], v[244:247], v[232:235], v[148:151]
	v_mfma_f32_16x16x32_bf16 v[152:155], v[248:251], v[232:235], v[152:155]
	v_mfma_f32_16x16x32_bf16 v[156:159], v[252:255], v[232:235], v[156:159]
	s_add_u32 s2, s2, 0x80
	s_addc_u32 s3, s3, 0
	s_add_u32 s6, s6, 0x80
	s_addc_u32 s7, s7, 0
	s_waitcnt lgkmcnt(0)
	v_mfma_f32_16x16x32_bf16 v[168:171], v[240:243], v[236:239], v[168:171]
	v_mfma_f32_16x16x32_bf16 v[172:175], v[244:247], v[236:239], v[172:175]
	v_mfma_f32_16x16x32_bf16 v[176:179], v[248:251], v[236:239], v[176:179]
	v_mfma_f32_16x16x32_bf16 v[180:183], v[252:255], v[236:239], v[180:183]
	s_waitcnt vmcnt(0)
	s_barrier
	ds_read_b128 v[184:187], v116 offset:53504
	ds_read_b128 v[204:207], v119 offset:20480
	ds_read_b128 v[208:211], v119 offset:22528
	ds_read_b128 v[212:215], v119 offset:24576
	ds_read_b128 v[216:219], v119 offset:26624
	ds_read_b128 v[188:191], v116 offset:55552
	ds_read_b128 v[192:195], v116 offset:57600
	ds_read_b128 v[196:199], v116 offset:59648
	ds_read_b128 v[200:203], v116 offset:61696
	s_waitcnt lgkmcnt(7)
	v_mfma_f32_16x16x32_bf16 v[0:3], v[204:207], v[184:187], v[0:3]
	s_add_u32 m0, s13, 0x9000
	s_nop 0
	global_load_lds_dwordx4 v165, s[24:25]
	s_waitcnt lgkmcnt(6)
	v_mfma_f32_16x16x32_bf16 v[4:7], v[208:211], v[184:187], v[4:7]
	s_add_u32 m0, s13, 0xa000
	v_add_u32_e32 v166, 0x2000, v165
	global_load_lds_dwordx4 v166, s[24:25]
	s_waitcnt lgkmcnt(5)
	v_mfma_f32_16x16x32_bf16 v[8:11], v[212:215], v[184:187], v[8:11]
	s_add_u32 m0, s13, 0xb000
	v_add_u32_e32 v166, 0x10000, v165
	global_load_lds_dwordx4 v166, s[24:25]
	s_waitcnt lgkmcnt(4)
	v_mfma_f32_16x16x32_bf16 v[12:15], v[216:219], v[184:187], v[12:15]
	s_add_u32 m0, s13, 0xc000
	v_add_u32_e32 v166, 0x12000, v165
	global_load_lds_dwordx4 v166, s[24:25]
	ds_read_b128 v[220:223], v118 offset:53504
	ds_read_b128 v[240:243], v160 offset:20480
	ds_read_b128 v[244:247], v160 offset:22528
	ds_read_b128 v[248:251], v160 offset:24576
	ds_read_b128 v[252:255], v160 offset:26624
	s_waitcnt lgkmcnt(8)
	v_mfma_f32_16x16x32_bf16 v[16:19], v[204:207], v[188:191], v[16:19]
	v_mfma_f32_16x16x32_bf16 v[20:23], v[208:211], v[188:191], v[20:23]
	v_mfma_f32_16x16x32_bf16 v[24:27], v[212:215], v[188:191], v[24:27]
	v_mfma_f32_16x16x32_bf16 v[28:31], v[216:219], v[188:191], v[28:31]
	ds_read_b128 v[224:227], v118 offset:55552
	ds_read_b128 v[228:231], v118 offset:57600
	ds_read_b128 v[232:235], v118 offset:59648
	ds_read_b128 v[236:239], v118 offset:61696
	s_waitcnt lgkmcnt(11)
	v_mfma_f32_16x16x32_bf16 v[32:35], v[204:207], v[192:195], v[32:35]
	v_mfma_f32_16x16x32_bf16 v[36:39], v[208:211], v[192:195], v[36:39]
	v_mfma_f32_16x16x32_bf16 v[40:43], v[212:215], v[192:195], v[40:43]
	v_mfma_f32_16x16x32_bf16 v[44:47], v[216:219], v[192:195], v[44:47]
	s_waitcnt lgkmcnt(10)
	v_mfma_f32_16x16x32_bf16 v[48:51], v[204:207], v[196:199], v[48:51]
	v_mfma_f32_16x16x32_bf16 v[52:55], v[208:211], v[196:199], v[52:55]
	v_mfma_f32_16x16x32_bf16 v[56:59], v[212:215], v[196:199], v[56:59]
	v_mfma_f32_16x16x32_bf16 v[60:63], v[216:219], v[196:199], v[60:63]
	s_waitcnt lgkmcnt(9)
	v_mfma_f32_16x16x32_bf16 v[64:67], v[204:207], v[200:203], v[64:67]
	v_mfma_f32_16x16x32_bf16 v[68:71], v[208:211], v[200:203], v[68:71]
	v_mfma_f32_16x16x32_bf16 v[72:75], v[212:215], v[200:203], v[72:75]
	v_mfma_f32_16x16x32_bf16 v[76:79], v[216:219], v[200:203], v[76:79]
	s_waitcnt lgkmcnt(7)
	v_mfma_f32_16x16x32_bf16 v[0:3], v[240:243], v[220:223], v[0:3]
	s_waitcnt lgkmcnt(6)
	v_mfma_f32_16x16x32_bf16 v[4:7], v[244:247], v[220:223], v[4:7]
	s_waitcnt lgkmcnt(5)
	v_mfma_f32_16x16x32_bf16 v[8:11], v[248:251], v[220:223], v[8:11]
	s_waitcnt lgkmcnt(4)
	v_mfma_f32_16x16x32_bf16 v[12:15], v[252:255], v[220:223], v[12:15]
	s_waitcnt lgkmcnt(3)
	v_mfma_f32_16x16x32_bf16 v[16:19], v[240:243], v[224:227], v[16:19]
	v_mfma_f32_16x16x32_bf16 v[20:23], v[244:247], v[224:227], v[20:23]
	v_mfma_f32_16x16x32_bf16 v[24:27], v[248:251], v[224:227], v[24:27]
	v_mfma_f32_16x16x32_bf16 v[28:31], v[252:255], v[224:227], v[28:31]
	s_waitcnt lgkmcnt(2)
	v_mfma_f32_16x16x32_bf16 v[32:35], v[240:243], v[228:231], v[32:35]
	v_mfma_f32_16x16x32_bf16 v[36:39], v[244:247], v[228:231], v[36:39]
	v_mfma_f32_16x16x32_bf16 v[40:43], v[248:251], v[228:231], v[40:43]
	v_mfma_f32_16x16x32_bf16 v[44:47], v[252:255], v[228:231], v[44:47]
	s_waitcnt lgkmcnt(1)
	v_mfma_f32_16x16x32_bf16 v[48:51], v[240:243], v[232:235], v[48:51]
	v_mfma_f32_16x16x32_bf16 v[52:55], v[244:247], v[232:235], v[52:55]
	v_mfma_f32_16x16x32_bf16 v[56:59], v[248:251], v[232:235], v[56:59]
	v_mfma_f32_16x16x32_bf16 v[60:63], v[252:255], v[232:235], v[60:63]
	s_add_u32 s24, s24, 0x80
	s_addc_u32 s25, s25, 0
	s_waitcnt lgkmcnt(0)
	v_mfma_f32_16x16x32_bf16 v[64:67], v[240:243], v[236:239], v[64:67]
	v_mfma_f32_16x16x32_bf16 v[68:71], v[244:247], v[236:239], v[68:71]
	v_mfma_f32_16x16x32_bf16 v[72:75], v[248:251], v[236:239], v[72:75]
	v_mfma_f32_16x16x32_bf16 v[76:79], v[252:255], v[236:239], v[76:79]
	s_cmp_eq_u32 s12, 1
	s_cselect_b32 s2, s20, s2
	s_cselect_b32 s3, s21, s3
	s_cselect_b32 s6, s22, s6
	s_cselect_b32 s7, s23, s7
	s_add_u32 s4, s22, 0x20000
	s_addc_u32 s32, s23, 0
	s_cmp_eq_u32 s12, 1
	s_cselect_b32 s24, s4, s24
	s_cselect_b32 s25, s32, s25
	s_add_u32 s4, s10, s11
	s_cmp_ge_u32 s4, s50
	s_cselect_b32 s4, s12, 0
	s_cmp_eq_u32 s4, 1
	s_cselect_b64 vcc, -1, 0
	s_waitcnt vmcnt(0)
	s_barrier
	ds_read_b128 v[184:187], v116 offset:53504
	ds_read_b128 v[204:207], v119 offset:36864
	ds_read_b128 v[208:211], v119 offset:38912
	ds_read_b128 v[212:215], v119 offset:40960
	ds_read_b128 v[216:219], v119 offset:43008
	ds_read_b128 v[188:191], v116 offset:55552
	ds_read_b128 v[192:195], v116 offset:57600
	ds_read_b128 v[196:199], v116 offset:59648
	ds_read_b128 v[200:203], v116 offset:61696
	s_waitcnt lgkmcnt(7)
	v_mfma_f32_16x16x32_bf16 v[80:83], v[204:207], v[184:187], v[80:83]
	s_cbranch_vccnz .Lggu0_sk0
	s_add_u32 m0, s13, 0x0
	s_nop 0
	global_load_lds_dwordx4 v161, s[2:3] sc1
.Lggu0_sk0:
	s_waitcnt lgkmcnt(6)
	v_mfma_f32_16x16x32_bf16 v[84:87], v[208:211], v[184:187], v[84:87]
	s_cbranch_vccnz .Lggu0_sk1
	s_add_u32 m0, s13, 0x1000
	v_add_u32_e32 v166, 0x10000, v161
	global_load_lds_dwordx4 v166, s[2:3] sc1
.Lggu0_sk1:
	s_waitcnt lgkmcnt(5)
	v_mfma_f32_16x16x32_bf16 v[88:91], v[212:215], v[184:187], v[88:91]
	s_cbranch_vccnz .Lggu0_sk2
	s_add_u32 m0, s13, 0x2000
	v_add_u32_e32 v166, 0x20000, v161
	global_load_lds_dwordx4 v166, s[2:3] sc1
.Lggu0_sk2:
	s_waitcnt lgkmcnt(4)
	v_mfma_f32_16x16x32_bf16 v[92:95], v[216:219], v[184:187], v[92:95]
	s_cbranch_vccnz .Lggu0_sk3
	s_add_u32 m0, s13, 0x3000
	v_add_u32_e32 v166, 0x30000, v161
	global_load_lds_dwordx4 v166, s[2:3] sc1
.Lggu0_sk3:
	ds_read_b128 v[220:223], v118 offset:53504
	ds_read_b128 v[240:243], v160 offset:36864
	ds_read_b128 v[244:247], v160 offset:38912
	ds_read_b128 v[248:251], v160 offset:40960
	ds_read_b128 v[252:255], v160 offset:43008
	s_waitcnt lgkmcnt(8)
	v_mfma_f32_16x16x32_bf16 v[96:99], v[204:207], v[188:191], v[96:99]
	s_cbranch_vccnz .Lggu0_sk4
	s_add_u32 m0, s13, 0x4000
	v_add_u32_e32 v166, 0x40000, v161
	global_load_lds_dwordx4 v166, s[2:3] sc1
.Lggu0_sk4:
	v_mfma_f32_16x16x32_bf16 v[100:103], v[208:211], v[188:191], v[100:103]
	s_cbranch_vccnz .Lggu0_sk5
	s_add_u32 m0, s13, 0x5000
	s_nop 0
	global_load_lds_dwordx4 v165, s[6:7]
.Lggu0_sk5:
	v_mfma_f32_16x16x32_bf16 v[104:107], v[212:215], v[188:191], v[104:107]
	s_cbranch_vccnz .Lggu0_sk6
	s_add_u32 m0, s13, 0x6000
	v_add_u32_e32 v166, 0x2000, v165
	global_load_lds_dwordx4 v166, s[6:7]
.Lggu0_sk6:
	v_mfma_f32_16x16x32_bf16 v[108:111], v[216:219], v[188:191], v[108:111]
	s_cbranch_vccnz .Lggu0_sk7
	s_add_u32 m0, s13, 0x7000
	v_add_u32_e32 v166, 0x10000, v165
	global_load_lds_dwordx4 v166, s[6:7]
.Lggu0_sk7:
	ds_read_b128 v[224:227], v118 offset:55552
	ds_read_b128 v[228:231], v118 offset:57600
	ds_read_b128 v[232:235], v118 offset:59648
	ds_read_b128 v[236:239], v118 offset:61696
	s_waitcnt lgkmcnt(11)
	v_mfma_f32_16x16x32_bf16 v[112:115], v[204:207], v[192:195], v[112:115]
	s_cbranch_vccnz .Lggu0_sk8
	s_add_u32 m0, s13, 0x8000
	v_add_u32_e32 v166, 0x12000, v165
	global_load_lds_dwordx4 v166, s[6:7]
.Lggu0_sk8:
	v_mfma_f32_16x16x32_bf16 v[120:123], v[208:211], v[192:195], v[120:123]
	v_mfma_f32_16x16x32_bf16 v[124:127], v[212:215], v[192:195], v[124:127]
	v_mfma_f32_16x16x32_bf16 v[140:143], v[216:219], v[192:195], v[140:143]
	s_waitcnt lgkmcnt(10)
	v_mfma_f32_16x16x32_bf16 v[144:147], v[204:207], v[196:199], v[144:147]
	v_mfma_f32_16x16x32_bf16 v[148:151], v[208:211], v[196:199], v[148:151]
	v_mfma_f32_16x16x32_bf16 v[152:155], v[212:215], v[196:199], v[152:155]
	v_mfma_f32_16x16x32_bf16 v[156:159], v[216:219], v[196:199], v[156:159]
	s_waitcnt lgkmcnt(9)
	v_mfma_f32_16x16x32_bf16 v[168:171], v[204:207], v[200:203], v[168:171]
	v_mfma_f32_16x16x32_bf16 v[172:175], v[208:211], v[200:203], v[172:175]
	v_mfma_f32_16x16x32_bf16 v[176:179], v[212:215], v[200:203], v[176:179]
	v_mfma_f32_16x16x32_bf16 v[180:183], v[216:219], v[200:203], v[180:183]
	s_waitcnt lgkmcnt(7)
	v_mfma_f32_16x16x32_bf16 v[80:83], v[240:243], v[220:223], v[80:83]
	s_waitcnt lgkmcnt(6)
	v_mfma_f32_16x16x32_bf16 v[84:87], v[244:247], v[220:223], v[84:87]
	s_waitcnt lgkmcnt(5)
	v_mfma_f32_16x16x32_bf16 v[88:91], v[248:251], v[220:223], v[88:91]
	s_waitcnt lgkmcnt(4)
	v_mfma_f32_16x16x32_bf16 v[92:95], v[252:255], v[220:223], v[92:95]
	s_waitcnt lgkmcnt(3)
	v_mfma_f32_16x16x32_bf16 v[96:99], v[240:243], v[224:227], v[96:99]
	v_mfma_f32_16x16x32_bf16 v[100:103], v[244:247], v[224:227], v[100:103]
	v_mfma_f32_16x16x32_bf16 v[104:107], v[248:251], v[224:227], v[104:107]
	v_mfma_f32_16x16x32_bf16 v[108:111], v[252:255], v[224:227], v[108:111]
	s_waitcnt lgkmcnt(2)
	v_mfma_f32_16x16x32_bf16 v[112:115], v[240:243], v[228:231], v[112:115]
	v_mfma_f32_16x16x32_bf16 v[120:123], v[244:247], v[228:231], v[120:123]
	v_mfma_f32_16x16x32_bf16 v[124:127], v[248:251], v[228:231], v[124:127]
	v_mfma_f32_16x16x32_bf16 v[140:143], v[252:255], v[228:231], v[140:143]
	s_waitcnt lgkmcnt(1)
	v_mfma_f32_16x16x32_bf16 v[144:147], v[240:243], v[232:235], v[144:147]
	v_mfma_f32_16x16x32_bf16 v[148:151], v[244:247], v[232:235], v[148:151]
	v_mfma_f32_16x16x32_bf16 v[152:155], v[248:251], v[232:235], v[152:155]
	v_mfma_f32_16x16x32_bf16 v[156:159], v[252:255], v[232:235], v[156:159]
	s_add_u32 s2, s2, 0x80
	s_addc_u32 s3, s3, 0
	s_add_u32 s6, s6, 0x80
	s_addc_u32 s7, s7, 0
	s_waitcnt lgkmcnt(0)
	v_mfma_f32_16x16x32_bf16 v[168:171], v[240:243], v[236:239], v[168:171]
	v_mfma_f32_16x16x32_bf16 v[172:175], v[244:247], v[236:239], v[172:175]
	v_mfma_f32_16x16x32_bf16 v[176:179], v[248:251], v[236:239], v[176:179]
	v_mfma_f32_16x16x32_bf16 v[180:183], v[252:255], v[236:239], v[180:183]
	s_sub_u32 s12, s12, 1
	s_cmp_lg_u32 s12, 0
	s_cbranch_scc1 .Lggu0_pair
	s_and_b32 s4, s10, 7
	s_lshl_b32 s4, s4, 3
	s_bfe_u32 s14, s10, 0x30003
	s_or_b32 s14, s14, s4
	s_lshr_b32 s15, s10, 6
	s_mul_i32 s4, s14, 0xdc000
	s_lshl_b32 s32, s15, 8
	s_add_u32 s4, s4, s32
	s_add_u32 s8, s76, s4
	s_addc_u32 s9, s77, 0
	s_mov_b32 s44, s8
	s_mov_b32 s46, s9
	s_nop 7
	v_mul_f32_e32 v184, 0xbfb8aa3b, v0
	v_mul_f32_e32 v185, 0xbfb8aa3b, v1
	v_mul_f32_e32 v186, 0xbfb8aa3b, v2
	v_mul_f32_e32 v187, 0xbfb8aa3b, v3
	v_exp_f32_e32 v184, v184
	v_exp_f32_e32 v185, v185
	v_exp_f32_e32 v186, v186
	v_exp_f32_e32 v187, v187
	s_nop 0
	v_add_f32_e32 v184, 1.0, v184
	v_add_f32_e32 v185, 1.0, v185
	v_add_f32_e32 v186, 1.0, v186
	v_add_f32_e32 v187, 1.0, v187
	v_rcp_f32_e32 v184, v184
	v_rcp_f32_e32 v185, v185
	v_rcp_f32_e32 v186, v186
	v_rcp_f32_e32 v187, v187
	s_nop 0
	v_mul_f32_e32 v184, v0, v184
	v_mul_f32_e32 v185, v1, v185
	v_mul_f32_e32 v186, v2, v186
	v_mul_f32_e32 v187, v3, v187
	v_mul_f32_e32 v184, v4, v184
	v_mul_f32_e32 v185, v5, v185
	v_mul_f32_e32 v186, v6, v186
	v_mul_f32_e32 v187, v7, v187
	v_mul_f32_e32 v192, 0xbfb8aa3b, v8
	v_mul_f32_e32 v193, 0xbfb8aa3b, v9
	v_mul_f32_e32 v194, 0xbfb8aa3b, v10
	v_mul_f32_e32 v195, 0xbfb8aa3b, v11
	v_exp_f32_e32 v192, v192
	v_exp_f32_e32 v193, v193
	v_exp_f32_e32 v194, v194
	v_exp_f32_e32 v195, v195
	s_nop 0
	v_add_f32_e32 v192, 1.0, v192
	v_add_f32_e32 v193, 1.0, v193
	v_add_f32_e32 v194, 1.0, v194
	v_add_f32_e32 v195, 1.0, v195
	v_rcp_f32_e32 v192, v192
	v_rcp_f32_e32 v193, v193
	v_rcp_f32_e32 v194, v194
	v_rcp_f32_e32 v195, v195
	s_nop 0
	v_mul_f32_e32 v192, v8, v192
	v_mul_f32_e32 v193, v9, v193
	v_mul_f32_e32 v194, v10, v194
	v_mul_f32_e32 v195, v11, v195
	v_mul_f32_e32 v192, v12, v192
	v_mul_f32_e32 v193, v13, v193
	v_mul_f32_e32 v194, v14, v194
	v_mul_f32_e32 v195, v15, v195
	v_cvt_pk_bf16_f32 v200, v184, v185
	v_cvt_pk_bf16_f32 v201, v186, v187
	v_cvt_pk_bf16_f32 v202, v192, v193
	v_cvt_pk_bf16_f32 v203, v194, v195
	global_store_dwordx4 v167, v[200:203], s[8:9]
	s_add_u32 s8, s8, 0x16000
	s_addc_u32 s9, s9, 0
	v_mul_f32_e32 v184, 0xbfb8aa3b, v16
	v_mul_f32_e32 v185, 0xbfb8aa3b, v17
	v_mul_f32_e32 v186, 0xbfb8aa3b, v18
	v_mul_f32_e32 v187, 0xbfb8aa3b, v19
	v_exp_f32_e32 v184, v184
	v_exp_f32_e32 v185, v185
	v_exp_f32_e32 v186, v186
	v_exp_f32_e32 v187, v187
	s_nop 0
	v_add_f32_e32 v184, 1.0, v184
	v_add_f32_e32 v185, 1.0, v185
	v_add_f32_e32 v186, 1.0, v186
	v_add_f32_e32 v187, 1.0, v187
	v_rcp_f32_e32 v184, v184
	v_rcp_f32_e32 v185, v185
	v_rcp_f32_e32 v186, v186
	v_rcp_f32_e32 v187, v187
	s_nop 0
	v_mul_f32_e32 v184, v16, v184
	v_mul_f32_e32 v185, v17, v185
	v_mul_f32_e32 v186, v18, v186
	v_mul_f32_e32 v187, v19, v187
	v_mul_f32_e32 v184, v20, v184
	v_mul_f32_e32 v185, v21, v185
	v_mul_f32_e32 v186, v22, v186
	v_mul_f32_e32 v187, v23, v187
	v_mul_f32_e32 v192, 0xbfb8aa3b, v24
	v_mul_f32_e32 v193, 0xbfb8aa3b, v25
	v_mul_f32_e32 v194, 0xbfb8aa3b, v26
	v_mul_f32_e32 v195, 0xbfb8aa3b, v27
	v_exp_f32_e32 v192, v192
	v_exp_f32_e32 v193, v193
	v_exp_f32_e32 v194, v194
	v_exp_f32_e32 v195, v195
	s_nop 0
	v_add_f32_e32 v192, 1.0, v192
	v_add_f32_e32 v193, 1.0, v193
	v_add_f32_e32 v194, 1.0, v194
	v_add_f32_e32 v195, 1.0, v195
	v_rcp_f32_e32 v192, v192
	v_rcp_f32_e32 v193, v193
	v_rcp_f32_e32 v194, v194
	v_rcp_f32_e32 v195, v195
	s_nop 0
	v_mul_f32_e32 v192, v24, v192
	v_mul_f32_e32 v193, v25, v193
	v_mul_f32_e32 v194, v26, v194
	v_mul_f32_e32 v195, v27, v195
	v_mul_f32_e32 v192, v28, v192
	v_mul_f32_e32 v193, v29, v193
	v_mul_f32_e32 v194, v30, v194
	v_mul_f32_e32 v195, v31, v195
	v_cvt_pk_bf16_f32 v204, v184, v185
	v_cvt_pk_bf16_f32 v205, v186, v187
	v_cvt_pk_bf16_f32 v206, v192, v193
	v_cvt_pk_bf16_f32 v207, v194, v195
	global_store_dwordx4 v167, v[204:207], s[8:9]
	s_add_u32 s8, s8, 0x16000
	s_addc_u32 s9, s9, 0
	v_mul_f32_e32 v184, 0xbfb8aa3b, v32
	v_mul_f32_e32 v185, 0xbfb8aa3b, v33
	v_mul_f32_e32 v186, 0xbfb8aa3b, v34
	v_mul_f32_e32 v187, 0xbfb8aa3b, v35
	v_exp_f32_e32 v184, v184
	v_exp_f32_e32 v185, v185
	v_exp_f32_e32 v186, v186
	v_exp_f32_e32 v187, v187
	s_nop 0
	v_add_f32_e32 v184, 1.0, v184
	v_add_f32_e32 v185, 1.0, v185
	v_add_f32_e32 v186, 1.0, v186
	v_add_f32_e32 v187, 1.0, v187
	v_rcp_f32_e32 v184, v184
	v_rcp_f32_e32 v185, v185
	v_rcp_f32_e32 v186, v186
	v_rcp_f32_e32 v187, v187
	s_nop 0
	v_mul_f32_e32 v184, v32, v184
	v_mul_f32_e32 v185, v33, v185
	v_mul_f32_e32 v186, v34, v186
	v_mul_f32_e32 v187, v35, v187
	v_mul_f32_e32 v184, v36, v184
	v_mul_f32_e32 v185, v37, v185
	v_mul_f32_e32 v186, v38, v186
	v_mul_f32_e32 v187, v39, v187
	v_mul_f32_e32 v192, 0xbfb8aa3b, v40
	v_mul_f32_e32 v193, 0xbfb8aa3b, v41
	v_mul_f32_e32 v194, 0xbfb8aa3b, v42
	v_mul_f32_e32 v195, 0xbfb8aa3b, v43
	v_exp_f32_e32 v192, v192
	v_exp_f32_e32 v193, v193
	v_exp_f32_e32 v194, v194
	v_exp_f32_e32 v195, v195
	s_nop 0
	v_add_f32_e32 v192, 1.0, v192
	v_add_f32_e32 v193, 1.0, v193
	v_add_f32_e32 v194, 1.0, v194
	v_add_f32_e32 v195, 1.0, v195
	v_rcp_f32_e32 v192, v192
	v_rcp_f32_e32 v193, v193
	v_rcp_f32_e32 v194, v194
	v_rcp_f32_e32 v195, v195
	s_nop 0
	v_mul_f32_e32 v192, v40, v192
	v_mul_f32_e32 v193, v41, v193
	v_mul_f32_e32 v194, v42, v194
	v_mul_f32_e32 v195, v43, v195
	v_mul_f32_e32 v192, v44, v192
	v_mul_f32_e32 v193, v45, v193
	v_mul_f32_e32 v194, v46, v194
	v_mul_f32_e32 v195, v47, v195
	v_cvt_pk_bf16_f32 v208, v184, v185
	v_cvt_pk_bf16_f32 v209, v186, v187
	v_cvt_pk_bf16_f32 v210, v192, v193
	v_cvt_pk_bf16_f32 v211, v194, v195
	global_store_dwordx4 v167, v[208:211], s[8:9]
	s_add_u32 s8, s8, 0x16000
	s_addc_u32 s9, s9, 0
	v_mul_f32_e32 v184, 0xbfb8aa3b, v48
	v_mul_f32_e32 v185, 0xbfb8aa3b, v49
	v_mul_f32_e32 v186, 0xbfb8aa3b, v50
	v_mul_f32_e32 v187, 0xbfb8aa3b, v51
	v_exp_f32_e32 v184, v184
	v_exp_f32_e32 v185, v185
	v_exp_f32_e32 v186, v186
	v_exp_f32_e32 v187, v187
	s_nop 0
	v_add_f32_e32 v184, 1.0, v184
	v_add_f32_e32 v185, 1.0, v185
	v_add_f32_e32 v186, 1.0, v186
	v_add_f32_e32 v187, 1.0, v187
	v_rcp_f32_e32 v184, v184
	v_rcp_f32_e32 v185, v185
	v_rcp_f32_e32 v186, v186
	v_rcp_f32_e32 v187, v187
	s_nop 0
	v_mul_f32_e32 v184, v48, v184
	v_mul_f32_e32 v185, v49, v185
	v_mul_f32_e32 v186, v50, v186
	v_mul_f32_e32 v187, v51, v187
	v_mul_f32_e32 v184, v52, v184
	v_mul_f32_e32 v185, v53, v185
	v_mul_f32_e32 v186, v54, v186
	v_mul_f32_e32 v187, v55, v187
	v_mul_f32_e32 v192, 0xbfb8aa3b, v56
	v_mul_f32_e32 v193, 0xbfb8aa3b, v57
	v_mul_f32_e32 v194, 0xbfb8aa3b, v58
	v_mul_f32_e32 v195, 0xbfb8aa3b, v59
	v_exp_f32_e32 v192, v192
	v_exp_f32_e32 v193, v193
	v_exp_f32_e32 v194, v194
	v_exp_f32_e32 v195, v195
	s_nop 0
	v_add_f32_e32 v192, 1.0, v192
	v_add_f32_e32 v193, 1.0, v193
	v_add_f32_e32 v194, 1.0, v194
	v_add_f32_e32 v195, 1.0, v195
	v_rcp_f32_e32 v192, v192
	v_rcp_f32_e32 v193, v193
	v_rcp_f32_e32 v194, v194
	v_rcp_f32_e32 v195, v195
	s_nop 0
	v_mul_f32_e32 v192, v56, v192
	v_mul_f32_e32 v193, v57, v193
	v_mul_f32_e32 v194, v58, v194
	v_mul_f32_e32 v195, v59, v195
	v_mul_f32_e32 v192, v60, v192
	v_mul_f32_e32 v193, v61, v193
	v_mul_f32_e32 v194, v62, v194
	v_mul_f32_e32 v195, v63, v195
	v_cvt_pk_bf16_f32 v212, v184, v185
	v_cvt_pk_bf16_f32 v213, v186, v187
	v_cvt_pk_bf16_f32 v214, v192, v193
	v_cvt_pk_bf16_f32 v215, v194, v195
	global_store_dwordx4 v167, v[212:215], s[8:9]
	s_add_u32 s8, s8, 0x16000
	s_addc_u32 s9, s9, 0
	v_mul_f32_e32 v184, 0xbfb8aa3b, v64
	v_mul_f32_e32 v185, 0xbfb8aa3b, v65
	v_mul_f32_e32 v186, 0xbfb8aa3b, v66
	v_mul_f32_e32 v187, 0xbfb8aa3b, v67
	v_exp_f32_e32 v184, v184
	v_exp_f32_e32 v185, v185
	v_exp_f32_e32 v186, v186
	v_exp_f32_e32 v187, v187
	s_nop 0
	v_add_f32_e32 v184, 1.0, v184
	v_add_f32_e32 v185, 1.0, v185
	v_add_f32_e32 v186, 1.0, v186
	v_add_f32_e32 v187, 1.0, v187
	v_rcp_f32_e32 v184, v184
	v_rcp_f32_e32 v185, v185
	v_rcp_f32_e32 v186, v186
	v_rcp_f32_e32 v187, v187
	s_nop 0
	v_mul_f32_e32 v184, v64, v184
	v_mul_f32_e32 v185, v65, v185
	v_mul_f32_e32 v186, v66, v186
	v_mul_f32_e32 v187, v67, v187
	v_mul_f32_e32 v184, v68, v184
	v_mul_f32_e32 v185, v69, v185
	v_mul_f32_e32 v186, v70, v186
	v_mul_f32_e32 v187, v71, v187
	v_mul_f32_e32 v192, 0xbfb8aa3b, v72
	v_mul_f32_e32 v193, 0xbfb8aa3b, v73
	v_mul_f32_e32 v194, 0xbfb8aa3b, v74
	v_mul_f32_e32 v195, 0xbfb8aa3b, v75
	v_exp_f32_e32 v192, v192
	v_exp_f32_e32 v193, v193
	v_exp_f32_e32 v194, v194
	v_exp_f32_e32 v195, v195
	s_nop 0
	v_add_f32_e32 v192, 1.0, v192
	v_add_f32_e32 v193, 1.0, v193
	v_add_f32_e32 v194, 1.0, v194
	v_add_f32_e32 v195, 1.0, v195
	v_rcp_f32_e32 v192, v192
	v_rcp_f32_e32 v193, v193
	v_rcp_f32_e32 v194, v194
	v_rcp_f32_e32 v195, v195
	s_nop 0
	v_mul_f32_e32 v192, v72, v192
	v_mul_f32_e32 v193, v73, v193
	v_mul_f32_e32 v194, v74, v194
	v_mul_f32_e32 v195, v75, v195
	v_mul_f32_e32 v192, v76, v192
	v_mul_f32_e32 v193, v77, v193
	v_mul_f32_e32 v194, v78, v194
	v_mul_f32_e32 v195, v79, v195
	v_cvt_pk_bf16_f32 v216, v184, v185
	v_cvt_pk_bf16_f32 v217, v186, v187
	v_cvt_pk_bf16_f32 v218, v192, v193
	v_cvt_pk_bf16_f32 v219, v194, v195
	global_store_dwordx4 v167, v[216:219], s[8:9]
	s_add_u32 s8, s44, 0x80
	s_addc_u32 s9, s46, 0
	v_mul_f32_e32 v184, 0xbfb8aa3b, v80
	v_mul_f32_e32 v185, 0xbfb8aa3b, v81
	v_mul_f32_e32 v186, 0xbfb8aa3b, v82
	v_mul_f32_e32 v187, 0xbfb8aa3b, v83
	v_exp_f32_e32 v184, v184
	v_exp_f32_e32 v185, v185
	v_exp_f32_e32 v186, v186
	v_exp_f32_e32 v187, v187
	s_nop 0
	v_add_f32_e32 v184, 1.0, v184
	v_add_f32_e32 v185, 1.0, v185
	v_add_f32_e32 v186, 1.0, v186
	v_add_f32_e32 v187, 1.0, v187
	v_rcp_f32_e32 v184, v184
	v_rcp_f32_e32 v185, v185
	v_rcp_f32_e32 v186, v186
	v_rcp_f32_e32 v187, v187
	s_nop 0
	v_mul_f32_e32 v184, v80, v184
	v_mul_f32_e32 v185, v81, v185
	v_mul_f32_e32 v186, v82, v186
	v_mul_f32_e32 v187, v83, v187
	v_mul_f32_e32 v184, v84, v184
	v_mul_f32_e32 v185, v85, v185
	v_mul_f32_e32 v186, v86, v186
	v_mul_f32_e32 v187, v87, v187
	v_mul_f32_e32 v192, 0xbfb8aa3b, v88
	v_mul_f32_e32 v193, 0xbfb8aa3b, v89
	v_mul_f32_e32 v194, 0xbfb8aa3b, v90
	v_mul_f32_e32 v195, 0xbfb8aa3b, v91
	v_exp_f32_e32 v192, v192
	v_exp_f32_e32 v193, v193
	v_exp_f32_e32 v194, v194
	v_exp_f32_e32 v195, v195
	s_nop 0
	v_add_f32_e32 v192, 1.0, v192
	v_add_f32_e32 v193, 1.0, v193
	v_add_f32_e32 v194, 1.0, v194
	v_add_f32_e32 v195, 1.0, v195
	v_rcp_f32_e32 v192, v192
	v_rcp_f32_e32 v193, v193
	v_rcp_f32_e32 v194, v194
	v_rcp_f32_e32 v195, v195
	s_nop 0
	v_mul_f32_e32 v192, v88, v192
	v_mul_f32_e32 v193, v89, v193
	v_mul_f32_e32 v194, v90, v194
	v_mul_f32_e32 v195, v91, v195
	v_mul_f32_e32 v192, v92, v192
	v_mul_f32_e32 v193, v93, v193
	v_mul_f32_e32 v194, v94, v194
	v_mul_f32_e32 v195, v95, v195
	v_cvt_pk_bf16_f32 v200, v184, v185
	v_cvt_pk_bf16_f32 v201, v186, v187
	v_cvt_pk_bf16_f32 v202, v192, v193
	v_cvt_pk_bf16_f32 v203, v194, v195
	global_store_dwordx4 v167, v[200:203], s[8:9]
	s_add_u32 s8, s8, 0x16000
	s_addc_u32 s9, s9, 0
	v_mul_f32_e32 v184, 0xbfb8aa3b, v96
	v_mul_f32_e32 v185, 0xbfb8aa3b, v97
	v_mul_f32_e32 v186, 0xbfb8aa3b, v98
	v_mul_f32_e32 v187, 0xbfb8aa3b, v99
	v_exp_f32_e32 v184, v184
	v_exp_f32_e32 v185, v185
	v_exp_f32_e32 v186, v186
	v_exp_f32_e32 v187, v187
	s_nop 0
	v_add_f32_e32 v184, 1.0, v184
	v_add_f32_e32 v185, 1.0, v185
	v_add_f32_e32 v186, 1.0, v186
	v_add_f32_e32 v187, 1.0, v187
	v_rcp_f32_e32 v184, v184
	v_rcp_f32_e32 v185, v185
	v_rcp_f32_e32 v186, v186
	v_rcp_f32_e32 v187, v187
	s_nop 0
	v_mul_f32_e32 v184, v96, v184
	v_mul_f32_e32 v185, v97, v185
	v_mul_f32_e32 v186, v98, v186
	v_mul_f32_e32 v187, v99, v187
	v_mul_f32_e32 v184, v100, v184
	v_mul_f32_e32 v185, v101, v185
	v_mul_f32_e32 v186, v102, v186
	v_mul_f32_e32 v187, v103, v187
	v_mul_f32_e32 v192, 0xbfb8aa3b, v104
	v_mul_f32_e32 v193, 0xbfb8aa3b, v105
	v_mul_f32_e32 v194, 0xbfb8aa3b, v106
	v_mul_f32_e32 v195, 0xbfb8aa3b, v107
	v_exp_f32_e32 v192, v192
	v_exp_f32_e32 v193, v193
	v_exp_f32_e32 v194, v194
	v_exp_f32_e32 v195, v195
	s_nop 0
	v_add_f32_e32 v192, 1.0, v192
	v_add_f32_e32 v193, 1.0, v193
	v_add_f32_e32 v194, 1.0, v194
	v_add_f32_e32 v195, 1.0, v195
	v_rcp_f32_e32 v192, v192
	v_rcp_f32_e32 v193, v193
	v_rcp_f32_e32 v194, v194
	v_rcp_f32_e32 v195, v195
	s_nop 0
	v_mul_f32_e32 v192, v104, v192
	v_mul_f32_e32 v193, v105, v193
	v_mul_f32_e32 v194, v106, v194
	v_mul_f32_e32 v195, v107, v195
	v_mul_f32_e32 v192, v108, v192
	v_mul_f32_e32 v193, v109, v193
	v_mul_f32_e32 v194, v110, v194
	v_mul_f32_e32 v195, v111, v195
	v_cvt_pk_bf16_f32 v204, v184, v185
	v_cvt_pk_bf16_f32 v205, v186, v187
	v_cvt_pk_bf16_f32 v206, v192, v193
	v_cvt_pk_bf16_f32 v207, v194, v195
	global_store_dwordx4 v167, v[204:207], s[8:9]
	s_add_u32 s8, s8, 0x16000
	s_addc_u32 s9, s9, 0
	v_mul_f32_e32 v184, 0xbfb8aa3b, v112
	v_mul_f32_e32 v185, 0xbfb8aa3b, v113
	v_mul_f32_e32 v186, 0xbfb8aa3b, v114
	v_mul_f32_e32 v187, 0xbfb8aa3b, v115
	v_exp_f32_e32 v184, v184
	v_exp_f32_e32 v185, v185
	v_exp_f32_e32 v186, v186
	v_exp_f32_e32 v187, v187
	s_nop 0
	v_add_f32_e32 v184, 1.0, v184
	v_add_f32_e32 v185, 1.0, v185
	v_add_f32_e32 v186, 1.0, v186
	v_add_f32_e32 v187, 1.0, v187
	v_rcp_f32_e32 v184, v184
	v_rcp_f32_e32 v185, v185
	v_rcp_f32_e32 v186, v186
	v_rcp_f32_e32 v187, v187
	s_nop 0
	v_mul_f32_e32 v184, v112, v184
	v_mul_f32_e32 v185, v113, v185
	v_mul_f32_e32 v186, v114, v186
	v_mul_f32_e32 v187, v115, v187
	v_mul_f32_e32 v184, v120, v184
	v_mul_f32_e32 v185, v121, v185
	v_mul_f32_e32 v186, v122, v186
	v_mul_f32_e32 v187, v123, v187
	v_mul_f32_e32 v192, 0xbfb8aa3b, v124
	v_mul_f32_e32 v193, 0xbfb8aa3b, v125
	v_mul_f32_e32 v194, 0xbfb8aa3b, v126
	v_mul_f32_e32 v195, 0xbfb8aa3b, v127
	v_exp_f32_e32 v192, v192
	v_exp_f32_e32 v193, v193
	v_exp_f32_e32 v194, v194
	v_exp_f32_e32 v195, v195
	s_nop 0
	v_add_f32_e32 v192, 1.0, v192
	v_add_f32_e32 v193, 1.0, v193
	v_add_f32_e32 v194, 1.0, v194
	v_add_f32_e32 v195, 1.0, v195
	v_rcp_f32_e32 v192, v192
	v_rcp_f32_e32 v193, v193
	v_rcp_f32_e32 v194, v194
	v_rcp_f32_e32 v195, v195
	s_nop 0
	v_mul_f32_e32 v192, v124, v192
	v_mul_f32_e32 v193, v125, v193
	v_mul_f32_e32 v194, v126, v194
	v_mul_f32_e32 v195, v127, v195
	v_mul_f32_e32 v192, v140, v192
	v_mul_f32_e32 v193, v141, v193
	v_mul_f32_e32 v194, v142, v194
	v_mul_f32_e32 v195, v143, v195
	v_cvt_pk_bf16_f32 v208, v184, v185
	v_cvt_pk_bf16_f32 v209, v186, v187
	v_cvt_pk_bf16_f32 v210, v192, v193
	v_cvt_pk_bf16_f32 v211, v194, v195
	global_store_dwordx4 v167, v[208:211], s[8:9]
	s_add_u32 s8, s8, 0x16000
	s_addc_u32 s9, s9, 0
	v_mul_f32_e32 v184, 0xbfb8aa3b, v144
	v_mul_f32_e32 v185, 0xbfb8aa3b, v145
	v_mul_f32_e32 v186, 0xbfb8aa3b, v146
	v_mul_f32_e32 v187, 0xbfb8aa3b, v147
	v_exp_f32_e32 v184, v184
	v_exp_f32_e32 v185, v185
	v_exp_f32_e32 v186, v186
	v_exp_f32_e32 v187, v187
	s_nop 0
	v_add_f32_e32 v184, 1.0, v184
	v_add_f32_e32 v185, 1.0, v185
	v_add_f32_e32 v186, 1.0, v186
	v_add_f32_e32 v187, 1.0, v187
	v_rcp_f32_e32 v184, v184
	v_rcp_f32_e32 v185, v185
	v_rcp_f32_e32 v186, v186
	v_rcp_f32_e32 v187, v187
	s_nop 0
	v_mul_f32_e32 v184, v144, v184
	v_mul_f32_e32 v185, v145, v185
	v_mul_f32_e32 v186, v146, v186
	v_mul_f32_e32 v187, v147, v187
	v_mul_f32_e32 v184, v148, v184
	v_mul_f32_e32 v185, v149, v185
	v_mul_f32_e32 v186, v150, v186
	v_mul_f32_e32 v187, v151, v187
	v_mul_f32_e32 v192, 0xbfb8aa3b, v152
	v_mul_f32_e32 v193, 0xbfb8aa3b, v153
	v_mul_f32_e32 v194, 0xbfb8aa3b, v154
	v_mul_f32_e32 v195, 0xbfb8aa3b, v155
	v_exp_f32_e32 v192, v192
	v_exp_f32_e32 v193, v193
	v_exp_f32_e32 v194, v194
	v_exp_f32_e32 v195, v195
	s_nop 0
	v_add_f32_e32 v192, 1.0, v192
	v_add_f32_e32 v193, 1.0, v193
	v_add_f32_e32 v194, 1.0, v194
	v_add_f32_e32 v195, 1.0, v195
	v_rcp_f32_e32 v192, v192
	v_rcp_f32_e32 v193, v193
	v_rcp_f32_e32 v194, v194
	v_rcp_f32_e32 v195, v195
	s_nop 0
	v_mul_f32_e32 v192, v152, v192
	v_mul_f32_e32 v193, v153, v193
	v_mul_f32_e32 v194, v154, v194
	v_mul_f32_e32 v195, v155, v195
	v_mul_f32_e32 v192, v156, v192
	v_mul_f32_e32 v193, v157, v193
	v_mul_f32_e32 v194, v158, v194
	v_mul_f32_e32 v195, v159, v195
	v_cvt_pk_bf16_f32 v212, v184, v185
	v_cvt_pk_bf16_f32 v213, v186, v187
	v_cvt_pk_bf16_f32 v214, v192, v193
	v_cvt_pk_bf16_f32 v215, v194, v195
	global_store_dwordx4 v167, v[212:215], s[8:9]
	s_add_u32 s8, s8, 0x16000
	s_addc_u32 s9, s9, 0
	v_mul_f32_e32 v184, 0xbfb8aa3b, v168
	v_mul_f32_e32 v185, 0xbfb8aa3b, v169
	v_mul_f32_e32 v186, 0xbfb8aa3b, v170
	v_mul_f32_e32 v187, 0xbfb8aa3b, v171
	v_exp_f32_e32 v184, v184
	v_exp_f32_e32 v185, v185
	v_exp_f32_e32 v186, v186
	v_exp_f32_e32 v187, v187
	s_nop 0
	v_add_f32_e32 v184, 1.0, v184
	v_add_f32_e32 v185, 1.0, v185
	v_add_f32_e32 v186, 1.0, v186
	v_add_f32_e32 v187, 1.0, v187
	v_rcp_f32_e32 v184, v184
	v_rcp_f32_e32 v185, v185
	v_rcp_f32_e32 v186, v186
	v_rcp_f32_e32 v187, v187
	s_nop 0
	v_mul_f32_e32 v184, v168, v184
	v_mul_f32_e32 v185, v169, v185
	v_mul_f32_e32 v186, v170, v186
	v_mul_f32_e32 v187, v171, v187
	v_mul_f32_e32 v184, v172, v184
	v_mul_f32_e32 v185, v173, v185
	v_mul_f32_e32 v186, v174, v186
	v_mul_f32_e32 v187, v175, v187
	v_mul_f32_e32 v192, 0xbfb8aa3b, v176
	v_mul_f32_e32 v193, 0xbfb8aa3b, v177
	v_mul_f32_e32 v194, 0xbfb8aa3b, v178
	v_mul_f32_e32 v195, 0xbfb8aa3b, v179
	v_exp_f32_e32 v192, v192
	v_exp_f32_e32 v193, v193
	v_exp_f32_e32 v194, v194
	v_exp_f32_e32 v195, v195
	s_nop 0
	v_add_f32_e32 v192, 1.0, v192
	v_add_f32_e32 v193, 1.0, v193
	v_add_f32_e32 v194, 1.0, v194
	v_add_f32_e32 v195, 1.0, v195
	v_rcp_f32_e32 v192, v192
	v_rcp_f32_e32 v193, v193
	v_rcp_f32_e32 v194, v194
	v_rcp_f32_e32 v195, v195
	s_nop 0
	v_mul_f32_e32 v192, v176, v192
	v_mul_f32_e32 v193, v177, v193
	v_mul_f32_e32 v194, v178, v194
	v_mul_f32_e32 v195, v179, v195
	v_mul_f32_e32 v192, v180, v192
	v_mul_f32_e32 v193, v181, v193
	v_mul_f32_e32 v194, v182, v194
	v_mul_f32_e32 v195, v183, v195
	v_cvt_pk_bf16_f32 v216, v184, v185
	v_cvt_pk_bf16_f32 v217, v186, v187
	v_cvt_pk_bf16_f32 v218, v192, v193
	v_cvt_pk_bf16_f32 v219, v194, v195
	global_store_dwordx4 v167, v[216:219], s[8:9]
	s_mov_b32 s48, 1
	s_add_u32 s10, s10, s11
	s_cmp_lt_u32 s10, s50
	s_cbranch_scc1 .Lggu0_tile

.Lgdn0_pair:
	s_waitcnt vmcnt(0)
	s_barrier
	ds_read_b128 v[80:83], v204 offset:0
	ds_read_b128 v[100:103], v206 offset:20480
	ds_read_b128 v[104:107], v206 offset:22528
	ds_read_b128 v[108:111], v206 offset:24576
	ds_read_b128 v[112:115], v206 offset:26624
	ds_read_b128 v[84:87], v204 offset:2048
	ds_read_b128 v[88:91], v204 offset:4096
	ds_read_b128 v[92:95], v204 offset:6144
	ds_read_b128 v[96:99], v204 offset:8192
	s_add_u32 m0, s13, 0xd100
	s_waitcnt lgkmcnt(7)
	v_mfma_f32_16x16x32_bf16 v[0:3], v[100:103], v[80:83], v[0:3]
	global_load_lds_dwordx4 v208, s[2:3] sc1
	s_add_u32 m0, s13, 0xe100
	s_waitcnt lgkmcnt(6)
	v_mfma_f32_16x16x32_bf16 v[4:7], v[104:107], v[80:83], v[4:7]
	global_load_lds_dwordx4 v209, s[2:3] sc1
	s_add_u32 m0, s13, 0xf100
	s_waitcnt lgkmcnt(5)
	v_mfma_f32_16x16x32_bf16 v[8:11], v[108:111], v[80:83], v[8:11]
	global_load_lds_dwordx4 v210, s[2:3] sc1
	s_add_u32 m0, s13, 0x10100
	s_waitcnt lgkmcnt(4)
	v_mfma_f32_16x16x32_bf16 v[12:15], v[112:115], v[80:83], v[12:15]
	global_load_lds_dwordx4 v211, s[2:3] sc1
	s_add_u32 m0, s13, 0x11100
	ds_read_b128 v[168:171], v205 offset:0
	ds_read_b128 v[188:191], v207 offset:20480
	ds_read_b128 v[192:195], v207 offset:22528
	ds_read_b128 v[196:199], v207 offset:24576
	ds_read_b128 v[200:203], v207 offset:26624
	s_waitcnt lgkmcnt(8)
	v_mfma_f32_16x16x32_bf16 v[16:19], v[100:103], v[84:87], v[16:19]
	global_load_lds_dwordx4 v212, s[2:3] sc1
	s_add_u32 m0, s13, 0x9000
	v_mfma_f32_16x16x32_bf16 v[20:23], v[104:107], v[84:87], v[20:23]
	global_load_lds_dwordx4 v213, s[6:7]
	s_add_u32 m0, s13, 0xa000
	v_mfma_f32_16x16x32_bf16 v[24:27], v[108:111], v[84:87], v[24:27]
	global_load_lds_dwordx4 v214, s[6:7]
	s_add_u32 m0, s13, 0xb000
	v_mfma_f32_16x16x32_bf16 v[28:31], v[112:115], v[84:87], v[28:31]
	global_load_lds_dwordx4 v215, s[6:7]
	s_add_u32 m0, s13, 0xc000
	ds_read_b128 v[172:175], v205 offset:2048
	ds_read_b128 v[176:179], v205 offset:4096
	ds_read_b128 v[180:183], v205 offset:6144
	ds_read_b128 v[184:187], v205 offset:8192
	s_waitcnt lgkmcnt(11)
	v_mfma_f32_16x16x32_bf16 v[32:35], v[100:103], v[88:91], v[32:35]
	global_load_lds_dwordx4 v216, s[6:7]
	v_mfma_f32_16x16x32_bf16 v[36:39], v[104:107], v[88:91], v[36:39]
	v_mfma_f32_16x16x32_bf16 v[40:43], v[108:111], v[88:91], v[40:43]
	v_mfma_f32_16x16x32_bf16 v[44:47], v[112:115], v[88:91], v[44:47]
	s_waitcnt lgkmcnt(10)
	v_mfma_f32_16x16x32_bf16 v[48:51], v[100:103], v[92:95], v[48:51]
	v_mfma_f32_16x16x32_bf16 v[52:55], v[104:107], v[92:95], v[52:55]
	v_mfma_f32_16x16x32_bf16 v[56:59], v[108:111], v[92:95], v[56:59]
	v_mfma_f32_16x16x32_bf16 v[60:63], v[112:115], v[92:95], v[60:63]
	s_waitcnt lgkmcnt(9)
	v_mfma_f32_16x16x32_bf16 v[64:67], v[100:103], v[96:99], v[64:67]
	v_mfma_f32_16x16x32_bf16 v[68:71], v[104:107], v[96:99], v[68:71]
	v_mfma_f32_16x16x32_bf16 v[72:75], v[108:111], v[96:99], v[72:75]
	v_mfma_f32_16x16x32_bf16 v[76:79], v[112:115], v[96:99], v[76:79]
	s_waitcnt lgkmcnt(7)
	v_mfma_f32_16x16x32_bf16 v[0:3], v[188:191], v[168:171], v[0:3]
	s_waitcnt lgkmcnt(6)
	v_mfma_f32_16x16x32_bf16 v[4:7], v[192:195], v[168:171], v[4:7]
	s_waitcnt lgkmcnt(5)
	v_mfma_f32_16x16x32_bf16 v[8:11], v[196:199], v[168:171], v[8:11]
	s_waitcnt lgkmcnt(4)
	v_mfma_f32_16x16x32_bf16 v[12:15], v[200:203], v[168:171], v[12:15]
	s_waitcnt lgkmcnt(3)
	v_mfma_f32_16x16x32_bf16 v[16:19], v[188:191], v[172:175], v[16:19]
	v_mfma_f32_16x16x32_bf16 v[20:23], v[192:195], v[172:175], v[20:23]
	v_mfma_f32_16x16x32_bf16 v[24:27], v[196:199], v[172:175], v[24:27]
	v_mfma_f32_16x16x32_bf16 v[28:31], v[200:203], v[172:175], v[28:31]
	s_waitcnt lgkmcnt(2)
	v_mfma_f32_16x16x32_bf16 v[32:35], v[188:191], v[176:179], v[32:35]
	v_mfma_f32_16x16x32_bf16 v[36:39], v[192:195], v[176:179], v[36:39]
	v_mfma_f32_16x16x32_bf16 v[40:43], v[196:199], v[176:179], v[40:43]
	v_mfma_f32_16x16x32_bf16 v[44:47], v[200:203], v[176:179], v[44:47]
	s_waitcnt lgkmcnt(1)
	v_mfma_f32_16x16x32_bf16 v[48:51], v[188:191], v[180:183], v[48:51]
	v_mfma_f32_16x16x32_bf16 v[52:55], v[192:195], v[180:183], v[52:55]
	v_mfma_f32_16x16x32_bf16 v[56:59], v[196:199], v[180:183], v[56:59]
	v_mfma_f32_16x16x32_bf16 v[60:63], v[200:203], v[180:183], v[60:63]
	s_add_u32 s2, s2, 0x80
	s_addc_u32 s3, s3, 0
	s_add_u32 s6, s6, 0x80
	s_addc_u32 s7, s7, 0
	s_waitcnt lgkmcnt(0)
	v_mfma_f32_16x16x32_bf16 v[64:67], v[188:191], v[184:187], v[64:67]
	v_mfma_f32_16x16x32_bf16 v[68:71], v[192:195], v[184:187], v[68:71]
	v_mfma_f32_16x16x32_bf16 v[72:75], v[196:199], v[184:187], v[72:75]
	v_mfma_f32_16x16x32_bf16 v[76:79], v[200:203], v[184:187], v[76:79]
	s_cmp_eq_u32 s12, 1
	s_cselect_b32 s2, s20, s2
	s_cselect_b32 s3, s21, s3
	s_cselect_b32 s6, s22, s6
	s_cselect_b32 s7, s23, s7
	s_add_u32 s4, s10, s11
	s_cmp_ge_u32 s4, 0x200
	s_cselect_b32 s4, s12, 0
	s_cmp_eq_u32 s4, 1
	s_cselect_b64 vcc, -1, 0
	s_waitcnt vmcnt(0)
	s_barrier
	ds_read_b128 v[80:83], v204 offset:53504
	ds_read_b128 v[100:103], v206 offset:36864
	ds_read_b128 v[104:107], v206 offset:38912
	ds_read_b128 v[108:111], v206 offset:40960
	ds_read_b128 v[112:115], v206 offset:43008
	ds_read_b128 v[84:87], v204 offset:55552
	ds_read_b128 v[88:91], v204 offset:57600
	ds_read_b128 v[92:95], v204 offset:59648
	ds_read_b128 v[96:99], v204 offset:61696
	s_add_u32 m0, s13, 0x0
	s_waitcnt lgkmcnt(7)
	v_mfma_f32_16x16x32_bf16 v[0:3], v[100:103], v[80:83], v[0:3]
	s_cbranch_vccnz .Lgdn0_sk0
	global_load_lds_dwordx4 v208, s[2:3] sc1
.Lgdn0_sk0:
	s_add_u32 m0, s13, 0x1000
	s_waitcnt lgkmcnt(6)
	v_mfma_f32_16x16x32_bf16 v[4:7], v[104:107], v[80:83], v[4:7]
	s_cbranch_vccnz .Lgdn0_sk1
	global_load_lds_dwordx4 v209, s[2:3] sc1
.Lgdn0_sk1:
	s_add_u32 m0, s13, 0x2000
	s_waitcnt lgkmcnt(5)
	v_mfma_f32_16x16x32_bf16 v[8:11], v[108:111], v[80:83], v[8:11]
	s_cbranch_vccnz .Lgdn0_sk2
	global_load_lds_dwordx4 v210, s[2:3] sc1
.Lgdn0_sk2:
	s_add_u32 m0, s13, 0x3000
	s_waitcnt lgkmcnt(4)
	v_mfma_f32_16x16x32_bf16 v[12:15], v[112:115], v[80:83], v[12:15]
	s_cbranch_vccnz .Lgdn0_sk3
	global_load_lds_dwordx4 v211, s[2:3] sc1
.Lgdn0_sk3:
	s_add_u32 m0, s13, 0x4000
	ds_read_b128 v[168:171], v205 offset:53504
	ds_read_b128 v[188:191], v207 offset:36864
	ds_read_b128 v[192:195], v207 offset:38912
	ds_read_b128 v[196:199], v207 offset:40960
	ds_read_b128 v[200:203], v207 offset:43008
	s_waitcnt lgkmcnt(8)
	v_mfma_f32_16x16x32_bf16 v[16:19], v[100:103], v[84:87], v[16:19]
	s_cbranch_vccnz .Lgdn0_sk4
	global_load_lds_dwordx4 v212, s[2:3] sc1
.Lgdn0_sk4:
	s_add_u32 m0, s13, 0x5000
	v_mfma_f32_16x16x32_bf16 v[20:23], v[104:107], v[84:87], v[20:23]
	s_cbranch_vccnz .Lgdn0_sk5
	global_load_lds_dwordx4 v213, s[6:7]
.Lgdn0_sk5:
	s_add_u32 m0, s13, 0x6000
	v_mfma_f32_16x16x32_bf16 v[24:27], v[108:111], v[84:87], v[24:27]
	s_cbranch_vccnz .Lgdn0_sk6
	global_load_lds_dwordx4 v214, s[6:7]
.Lgdn0_sk6:
	s_add_u32 m0, s13, 0x7000
	v_mfma_f32_16x16x32_bf16 v[28:31], v[112:115], v[84:87], v[28:31]
	s_cbranch_vccnz .Lgdn0_sk7
	global_load_lds_dwordx4 v215, s[6:7]
.Lgdn0_sk7:
	s_add_u32 m0, s13, 0x8000
	ds_read_b128 v[172:175], v205 offset:55552
	ds_read_b128 v[176:179], v205 offset:57600
	ds_read_b128 v[180:183], v205 offset:59648
	ds_read_b128 v[184:187], v205 offset:61696
	s_waitcnt lgkmcnt(11)
	v_mfma_f32_16x16x32_bf16 v[32:35], v[100:103], v[88:91], v[32:35]
	s_cbranch_vccnz .Lgdn0_sk8
	global_load_lds_dwordx4 v216, s[6:7]
.Lgdn0_sk8:
	v_mfma_f32_16x16x32_bf16 v[36:39], v[104:107], v[88:91], v[36:39]
	v_mfma_f32_16x16x32_bf16 v[40:43], v[108:111], v[88:91], v[40:43]
	v_mfma_f32_16x16x32_bf16 v[44:47], v[112:115], v[88:91], v[44:47]
	s_waitcnt lgkmcnt(10)
	v_mfma_f32_16x16x32_bf16 v[48:51], v[100:103], v[92:95], v[48:51]
	v_mfma_f32_16x16x32_bf16 v[52:55], v[104:107], v[92:95], v[52:55]
	v_mfma_f32_16x16x32_bf16 v[56:59], v[108:111], v[92:95], v[56:59]
	v_mfma_f32_16x16x32_bf16 v[60:63], v[112:115], v[92:95], v[60:63]
	s_waitcnt lgkmcnt(9)
	v_mfma_f32_16x16x32_bf16 v[64:67], v[100:103], v[96:99], v[64:67]
	v_mfma_f32_16x16x32_bf16 v[68:71], v[104:107], v[96:99], v[68:71]
	v_mfma_f32_16x16x32_bf16 v[72:75], v[108:111], v[96:99], v[72:75]
	v_mfma_f32_16x16x32_bf16 v[76:79], v[112:115], v[96:99], v[76:79]
	s_waitcnt lgkmcnt(7)
	v_mfma_f32_16x16x32_bf16 v[0:3], v[188:191], v[168:171], v[0:3]
	s_waitcnt lgkmcnt(6)
	v_mfma_f32_16x16x32_bf16 v[4:7], v[192:195], v[168:171], v[4:7]
	s_waitcnt lgkmcnt(5)
	v_mfma_f32_16x16x32_bf16 v[8:11], v[196:199], v[168:171], v[8:11]
	s_waitcnt lgkmcnt(4)
	v_mfma_f32_16x16x32_bf16 v[12:15], v[200:203], v[168:171], v[12:15]
	s_waitcnt lgkmcnt(3)
	v_mfma_f32_16x16x32_bf16 v[16:19], v[188:191], v[172:175], v[16:19]
	v_mfma_f32_16x16x32_bf16 v[20:23], v[192:195], v[172:175], v[20:23]
	v_mfma_f32_16x16x32_bf16 v[24:27], v[196:199], v[172:175], v[24:27]
	v_mfma_f32_16x16x32_bf16 v[28:31], v[200:203], v[172:175], v[28:31]
	s_waitcnt lgkmcnt(2)
	v_mfma_f32_16x16x32_bf16 v[32:35], v[188:191], v[176:179], v[32:35]
	v_mfma_f32_16x16x32_bf16 v[36:39], v[192:195], v[176:179], v[36:39]
	v_mfma_f32_16x16x32_bf16 v[40:43], v[196:199], v[176:179], v[40:43]
	v_mfma_f32_16x16x32_bf16 v[44:47], v[200:203], v[176:179], v[44:47]
	s_waitcnt lgkmcnt(1)
	v_mfma_f32_16x16x32_bf16 v[48:51], v[188:191], v[180:183], v[48:51]
	v_mfma_f32_16x16x32_bf16 v[52:55], v[192:195], v[180:183], v[52:55]
	v_mfma_f32_16x16x32_bf16 v[56:59], v[196:199], v[180:183], v[56:59]
	v_mfma_f32_16x16x32_bf16 v[60:63], v[200:203], v[180:183], v[60:63]
	s_add_u32 s2, s2, 0x80
	s_addc_u32 s3, s3, 0
	s_add_u32 s6, s6, 0x80
	s_addc_u32 s7, s7, 0
	s_waitcnt lgkmcnt(0)
	v_mfma_f32_16x16x32_bf16 v[64:67], v[188:191], v[184:187], v[64:67]
	v_mfma_f32_16x16x32_bf16 v[68:71], v[192:195], v[184:187], v[68:71]
	v_mfma_f32_16x16x32_bf16 v[72:75], v[196:199], v[184:187], v[72:75]
	v_mfma_f32_16x16x32_bf16 v[76:79], v[200:203], v[184:187], v[76:79]
	s_sub_u32 s12, s12, 1
	s_cmp_lg_u32 s12, 0
	s_cbranch_scc1 .Lgdn0_pair
	s_and_b32 s4, s10, 7
	s_lshl_b32 s4, s4, 3
	s_bfe_u32 s14, s10, 0x30003
	s_or_b32 s14, s14, s4
	s_lshr_b32 s15, s10, 6
	s_mul_i32 s4, s14, 0x50000
	s_lshl_b32 s32, s15, 8
	s_add_u32 s4, s4, s32
	s_add_u32 s8, s78, s4
	s_addc_u32 s9, s79, 0
	s_nop 7
	v_cvt_pk_bf16_f32 v80, v0, v1
	v_cvt_pk_bf16_f32 v81, v2, v3
	v_cvt_pk_bf16_f32 v82, v4, v5
	v_cvt_pk_bf16_f32 v83, v6, v7
	global_store_dwordx4 v217, v[80:83], s[8:9]
	v_cvt_pk_bf16_f32 v84, v8, v9
	v_cvt_pk_bf16_f32 v85, v10, v11
	v_cvt_pk_bf16_f32 v86, v12, v13
	v_cvt_pk_bf16_f32 v87, v14, v15
	global_store_dwordx4 v217, v[84:87], s[8:9] offset:64
	s_add_u32 s8, s8, 0x8000
	s_addc_u32 s9, s9, 0
	v_cvt_pk_bf16_f32 v88, v16, v17
	v_cvt_pk_bf16_f32 v89, v18, v19
	v_cvt_pk_bf16_f32 v90, v20, v21
	v_cvt_pk_bf16_f32 v91, v22, v23
	global_store_dwordx4 v217, v[88:91], s[8:9]
	v_cvt_pk_bf16_f32 v92, v24, v25
	v_cvt_pk_bf16_f32 v93, v26, v27
	v_cvt_pk_bf16_f32 v94, v28, v29
	v_cvt_pk_bf16_f32 v95, v30, v31
	global_store_dwordx4 v217, v[92:95], s[8:9] offset:64
	s_add_u32 s8, s8, 0x8000
	s_addc_u32 s9, s9, 0
	v_cvt_pk_bf16_f32 v96, v32, v33
	v_cvt_pk_bf16_f32 v97, v34, v35
	v_cvt_pk_bf16_f32 v98, v36, v37
	v_cvt_pk_bf16_f32 v99, v38, v39
	global_store_dwordx4 v217, v[96:99], s[8:9]
	v_cvt_pk_bf16_f32 v100, v40, v41
	v_cvt_pk_bf16_f32 v101, v42, v43
	v_cvt_pk_bf16_f32 v102, v44, v45
	v_cvt_pk_bf16_f32 v103, v46, v47
	global_store_dwordx4 v217, v[100:103], s[8:9] offset:64
	s_add_u32 s8, s8, 0x8000
	s_addc_u32 s9, s9, 0
	v_cvt_pk_bf16_f32 v104, v48, v49
	v_cvt_pk_bf16_f32 v105, v50, v51
	v_cvt_pk_bf16_f32 v106, v52, v53
	v_cvt_pk_bf16_f32 v107, v54, v55
	global_store_dwordx4 v217, v[104:107], s[8:9]
	v_cvt_pk_bf16_f32 v108, v56, v57
	v_cvt_pk_bf16_f32 v109, v58, v59
	v_cvt_pk_bf16_f32 v110, v60, v61
	v_cvt_pk_bf16_f32 v111, v62, v63
	global_store_dwordx4 v217, v[108:111], s[8:9] offset:64
	s_add_u32 s8, s8, 0x8000
	s_addc_u32 s9, s9, 0
	v_cvt_pk_bf16_f32 v112, v64, v65
	v_cvt_pk_bf16_f32 v113, v66, v67
	v_cvt_pk_bf16_f32 v114, v68, v69
	v_cvt_pk_bf16_f32 v115, v70, v71
	global_store_dwordx4 v217, v[112:115], s[8:9]
	v_cvt_pk_bf16_f32 v80, v72, v73
	v_cvt_pk_bf16_f32 v81, v74, v75
	v_cvt_pk_bf16_f32 v82, v76, v77
	v_cvt_pk_bf16_f32 v83, v78, v79
	global_store_dwordx4 v217, v[80:83], s[8:9] offset:64
	s_add_u32 s10, s10, s11
	s_cmp_lt_u32 s10, 0x200
	s_cbranch_scc1 .Lgdn0_tile

.Lgzin_pair:
	s_waitcnt vmcnt(0)
	s_barrier
	ds_read_b128 v[80:83], v204 offset:0
	ds_read_b128 v[100:103], v206 offset:20480
	ds_read_b128 v[104:107], v206 offset:22528
	ds_read_b128 v[108:111], v206 offset:24576
	ds_read_b128 v[112:115], v206 offset:26624
	ds_read_b128 v[84:87], v204 offset:2048
	ds_read_b128 v[88:91], v204 offset:4096
	ds_read_b128 v[92:95], v204 offset:6144
	ds_read_b128 v[96:99], v204 offset:8192
	s_add_u32 m0, s13, 0xd100
	s_waitcnt lgkmcnt(7)
	v_mfma_f32_16x16x32_bf16 v[0:3], v[100:103], v[80:83], v[0:3]
	global_load_lds_dwordx4 v208, s[2:3] sc1
	s_add_u32 m0, s13, 0xe100
	s_waitcnt lgkmcnt(6)
	v_mfma_f32_16x16x32_bf16 v[4:7], v[104:107], v[80:83], v[4:7]
	global_load_lds_dwordx4 v209, s[2:3] sc1
	s_add_u32 m0, s13, 0xf100
	s_waitcnt lgkmcnt(5)
	v_mfma_f32_16x16x32_bf16 v[8:11], v[108:111], v[80:83], v[8:11]
	global_load_lds_dwordx4 v210, s[2:3] sc1
	s_add_u32 m0, s13, 0x10100
	s_waitcnt lgkmcnt(4)
	v_mfma_f32_16x16x32_bf16 v[12:15], v[112:115], v[80:83], v[12:15]
	global_load_lds_dwordx4 v211, s[2:3] sc1
	s_add_u32 m0, s13, 0x11100
	ds_read_b128 v[168:171], v205 offset:0
	ds_read_b128 v[188:191], v207 offset:20480
	ds_read_b128 v[192:195], v207 offset:22528
	ds_read_b128 v[196:199], v207 offset:24576
	ds_read_b128 v[200:203], v207 offset:26624
	s_waitcnt lgkmcnt(8)
	v_mfma_f32_16x16x32_bf16 v[16:19], v[100:103], v[84:87], v[16:19]
	global_load_lds_dwordx4 v212, s[2:3] sc1
	s_add_u32 m0, s13, 0x9000
	v_mfma_f32_16x16x32_bf16 v[20:23], v[104:107], v[84:87], v[20:23]
	global_load_lds_dwordx4 v213, s[6:7]
	s_add_u32 m0, s13, 0xa000
	v_mfma_f32_16x16x32_bf16 v[24:27], v[108:111], v[84:87], v[24:27]
	global_load_lds_dwordx4 v214, s[6:7]
	s_add_u32 m0, s13, 0xb000
	v_mfma_f32_16x16x32_bf16 v[28:31], v[112:115], v[84:87], v[28:31]
	global_load_lds_dwordx4 v215, s[6:7]
	s_add_u32 m0, s13, 0xc000
	ds_read_b128 v[172:175], v205 offset:2048
	ds_read_b128 v[176:179], v205 offset:4096
	ds_read_b128 v[180:183], v205 offset:6144
	ds_read_b128 v[184:187], v205 offset:8192
	s_waitcnt lgkmcnt(11)
	v_mfma_f32_16x16x32_bf16 v[32:35], v[100:103], v[88:91], v[32:35]
	global_load_lds_dwordx4 v216, s[6:7]
	v_mfma_f32_16x16x32_bf16 v[36:39], v[104:107], v[88:91], v[36:39]
	v_mfma_f32_16x16x32_bf16 v[40:43], v[108:111], v[88:91], v[40:43]
	v_mfma_f32_16x16x32_bf16 v[44:47], v[112:115], v[88:91], v[44:47]
	s_waitcnt lgkmcnt(10)
	v_mfma_f32_16x16x32_bf16 v[48:51], v[100:103], v[92:95], v[48:51]
	v_mfma_f32_16x16x32_bf16 v[52:55], v[104:107], v[92:95], v[52:55]
	v_mfma_f32_16x16x32_bf16 v[56:59], v[108:111], v[92:95], v[56:59]
	v_mfma_f32_16x16x32_bf16 v[60:63], v[112:115], v[92:95], v[60:63]
	s_waitcnt lgkmcnt(9)
	v_mfma_f32_16x16x32_bf16 v[64:67], v[100:103], v[96:99], v[64:67]
	v_mfma_f32_16x16x32_bf16 v[68:71], v[104:107], v[96:99], v[68:71]
	v_mfma_f32_16x16x32_bf16 v[72:75], v[108:111], v[96:99], v[72:75]
	v_mfma_f32_16x16x32_bf16 v[76:79], v[112:115], v[96:99], v[76:79]
	s_waitcnt lgkmcnt(7)
	v_mfma_f32_16x16x32_bf16 v[0:3], v[188:191], v[168:171], v[0:3]
	s_waitcnt lgkmcnt(6)
	v_mfma_f32_16x16x32_bf16 v[4:7], v[192:195], v[168:171], v[4:7]
	s_waitcnt lgkmcnt(5)
	v_mfma_f32_16x16x32_bf16 v[8:11], v[196:199], v[168:171], v[8:11]
	s_waitcnt lgkmcnt(4)
	v_mfma_f32_16x16x32_bf16 v[12:15], v[200:203], v[168:171], v[12:15]
	s_waitcnt lgkmcnt(3)
	v_mfma_f32_16x16x32_bf16 v[16:19], v[188:191], v[172:175], v[16:19]
	v_mfma_f32_16x16x32_bf16 v[20:23], v[192:195], v[172:175], v[20:23]
	v_mfma_f32_16x16x32_bf16 v[24:27], v[196:199], v[172:175], v[24:27]
	v_mfma_f32_16x16x32_bf16 v[28:31], v[200:203], v[172:175], v[28:31]
	s_waitcnt lgkmcnt(2)
	v_mfma_f32_16x16x32_bf16 v[32:35], v[188:191], v[176:179], v[32:35]
	v_mfma_f32_16x16x32_bf16 v[36:39], v[192:195], v[176:179], v[36:39]
	v_mfma_f32_16x16x32_bf16 v[40:43], v[196:199], v[176:179], v[40:43]
	v_mfma_f32_16x16x32_bf16 v[44:47], v[200:203], v[176:179], v[44:47]
	s_waitcnt lgkmcnt(1)
	v_mfma_f32_16x16x32_bf16 v[48:51], v[188:191], v[180:183], v[48:51]
	v_mfma_f32_16x16x32_bf16 v[52:55], v[192:195], v[180:183], v[52:55]
	v_mfma_f32_16x16x32_bf16 v[56:59], v[196:199], v[180:183], v[56:59]
	v_mfma_f32_16x16x32_bf16 v[60:63], v[200:203], v[180:183], v[60:63]
	s_add_u32 s2, s2, 0x80
	s_addc_u32 s3, s3, 0
	s_add_u32 s6, s6, 0x80
	s_addc_u32 s7, s7, 0
	s_waitcnt lgkmcnt(0)
	v_mfma_f32_16x16x32_bf16 v[64:67], v[188:191], v[184:187], v[64:67]
	v_mfma_f32_16x16x32_bf16 v[68:71], v[192:195], v[184:187], v[68:71]
	v_mfma_f32_16x16x32_bf16 v[72:75], v[196:199], v[184:187], v[72:75]
	v_mfma_f32_16x16x32_bf16 v[76:79], v[200:203], v[184:187], v[76:79]
	s_cmp_eq_u32 s12, 1
	s_cselect_b32 s2, s20, s2
	s_cselect_b32 s3, s21, s3
	s_cselect_b32 s6, s22, s6
	s_cselect_b32 s7, s23, s7
	s_add_u32 s4, s10, s11
	s_cmp_ge_u32 s4, 0x600
	s_cselect_b32 s4, s12, 0
	s_cmp_eq_u32 s4, 1
	s_cselect_b64 vcc, -1, 0
	s_waitcnt vmcnt(0)
	s_barrier
	ds_read_b128 v[80:83], v204 offset:53504
	ds_read_b128 v[100:103], v206 offset:36864
	ds_read_b128 v[104:107], v206 offset:38912
	ds_read_b128 v[108:111], v206 offset:40960
	ds_read_b128 v[112:115], v206 offset:43008
	ds_read_b128 v[84:87], v204 offset:55552
	ds_read_b128 v[88:91], v204 offset:57600
	ds_read_b128 v[92:95], v204 offset:59648
	ds_read_b128 v[96:99], v204 offset:61696
	s_add_u32 m0, s13, 0x0
	s_waitcnt lgkmcnt(7)
	v_mfma_f32_16x16x32_bf16 v[0:3], v[100:103], v[80:83], v[0:3]
	s_cbranch_vccnz .Lgzin_sk0
	global_load_lds_dwordx4 v208, s[2:3] sc1

.Lgzin_sk8:
	v_mfma_f32_16x16x32_bf16 v[36:39], v[104:107], v[88:91], v[36:39]
	v_mfma_f32_16x16x32_bf16 v[40:43], v[108:111], v[88:91], v[40:43]
	v_mfma_f32_16x16x32_bf16 v[44:47], v[112:115], v[88:91], v[44:47]
	s_waitcnt lgkmcnt(10)
	v_mfma_f32_16x16x32_bf16 v[48:51], v[100:103], v[92:95], v[48:51]
	v_mfma_f32_16x16x32_bf16 v[52:55], v[104:107], v[92:95], v[52:55]
	v_mfma_f32_16x16x32_bf16 v[56:59], v[108:111], v[92:95], v[56:59]
	v_mfma_f32_16x16x32_bf16 v[60:63], v[112:115], v[92:95], v[60:63]
	s_waitcnt lgkmcnt(9)
	v_mfma_f32_16x16x32_bf16 v[64:67], v[100:103], v[96:99], v[64:67]
	v_mfma_f32_16x16x32_bf16 v[68:71], v[104:107], v[96:99], v[68:71]
	v_mfma_f32_16x16x32_bf16 v[72:75], v[108:111], v[96:99], v[72:75]
	v_mfma_f32_16x16x32_bf16 v[76:79], v[112:115], v[96:99], v[76:79]
	s_waitcnt lgkmcnt(7)
	v_mfma_f32_16x16x32_bf16 v[0:3], v[188:191], v[168:171], v[0:3]
	s_waitcnt lgkmcnt(6)
	v_mfma_f32_16x16x32_bf16 v[4:7], v[192:195], v[168:171], v[4:7]
	s_waitcnt lgkmcnt(5)
	v_mfma_f32_16x16x32_bf16 v[8:11], v[196:199], v[168:171], v[8:11]
	s_waitcnt lgkmcnt(4)
	v_mfma_f32_16x16x32_bf16 v[12:15], v[200:203], v[168:171], v[12:15]
	s_waitcnt lgkmcnt(3)
	v_mfma_f32_16x16x32_bf16 v[16:19], v[188:191], v[172:175], v[16:19]
	v_mfma_f32_16x16x32_bf16 v[20:23], v[192:195], v[172:175], v[20:23]
	v_mfma_f32_16x16x32_bf16 v[24:27], v[196:199], v[172:175], v[24:27]
	v_mfma_f32_16x16x32_bf16 v[28:31], v[200:203], v[172:175], v[28:31]
	s_waitcnt lgkmcnt(2)
	v_mfma_f32_16x16x32_bf16 v[32:35], v[188:191], v[176:179], v[32:35]
	v_mfma_f32_16x16x32_bf16 v[36:39], v[192:195], v[176:179], v[36:39]
	v_mfma_f32_16x16x32_bf16 v[40:43], v[196:199], v[176:179], v[40:43]
	v_mfma_f32_16x16x32_bf16 v[44:47], v[200:203], v[176:179], v[44:47]
	s_waitcnt lgkmcnt(1)
	v_mfma_f32_16x16x32_bf16 v[48:51], v[188:191], v[180:183], v[48:51]
	v_mfma_f32_16x16x32_bf16 v[52:55], v[192:195], v[180:183], v[52:55]
	v_mfma_f32_16x16x32_bf16 v[56:59], v[196:199], v[180:183], v[56:59]
	v_mfma_f32_16x16x32_bf16 v[60:63], v[200:203], v[180:183], v[60:63]
	s_add_u32 s2, s2, 0x80
	s_addc_u32 s3, s3, 0
	s_add_u32 s6, s6, 0x80
	s_addc_u32 s7, s7, 0
	s_waitcnt lgkmcnt(0)
	v_mfma_f32_16x16x32_bf16 v[64:67], v[188:191], v[184:187], v[64:67]
	v_mfma_f32_16x16x32_bf16 v[68:71], v[192:195], v[184:187], v[68:71]
	v_mfma_f32_16x16x32_bf16 v[72:75], v[196:199], v[184:187], v[72:75]
	v_mfma_f32_16x16x32_bf16 v[76:79], v[200:203], v[184:187], v[76:79]
	s_sub_u32 s12, s12, 1
	s_cmp_lg_u32 s12, 0
	s_cbranch_scc1 .Lgzin_pair
	s_and_b32 s4, s10, 7
	s_lshl_b32 s4, s4, 3
	s_bfe_u32 s14, s10, 0x30003
	s_or_b32 s14, s14, s4
	s_lshr_b32 s15, s10, 6
	s_mul_i32 s44, s14, 0xa0
	s_mul_i32 s4, s35, 0x50
	s_add_u32 s4, s4, s44
	v_add_u32_e32 v219, s4, v222
	s_nop 7
	s_lshl_b32 s46, s15, 7
	s_lshl_b32 s4, s36, 6
	s_add_u32 s46, s46, s4
	s_cmp_ge_u32 s46, 0xbc0
	s_cbranch_scc1 .Lgzin_z0_end
	s_cmp_lt_u32 s46, 0x200
	s_cbranch_scc1 .Lgzin_z0_q
	s_cmp_lt_u32 s46, 0x600
	s_cbranch_scc1 .Lgzin_z0_kv
	s_cmp_lt_u32 s46, 0x800
	s_cbranch_scc1 .Lgzin_z0_u
	s_mul_i32 s4, s44, 0x2f00
	s_lshl_b32 s32, s46, 2
	s_add_u32 s4, s4, s32
	s_add_u32 s8, s74, s4
	s_addc_u32 s9, s75, 0
	global_store_dwordx4 v218, v[0:3], s[8:9]
	global_store_dwordx4 v218, v[4:7], s[8:9] offset:16
	s_add_u32 s8, s8, 0x2f000
	s_addc_u32 s9, s9, 0
	global_store_dwordx4 v218, v[16:19], s[8:9]
	global_store_dwordx4 v218, v[20:23], s[8:9] offset:16
	s_add_u32 s8, s8, 0x2f000
	s_addc_u32 s9, s9, 0
	global_store_dwordx4 v218, v[32:35], s[8:9]
	global_store_dwordx4 v218, v[36:39], s[8:9] offset:16
	s_add_u32 s8, s8, 0x2f000
	s_addc_u32 s9, s9, 0
	global_store_dwordx4 v218, v[48:51], s[8:9]
	global_store_dwordx4 v218, v[52:55], s[8:9] offset:16
	s_add_u32 s8, s8, 0x2f000
	s_addc_u32 s9, s9, 0
	global_store_dwordx4 v218, v[64:67], s[8:9]
	global_store_dwordx4 v218, v[68:71], s[8:9] offset:16
	s_branch .Lgzin_z0_end
